# nt (streaming) cache hint on once-used epilogue traffic: P5 x loads, P8 X1 loads and y stores
# baseline (speedup 1.0000x reference)
.LBB0_1800:
	s_lshl_b32 s57, s64, 8
	s_add_i32 s57, s57, s79
	v_or_b32_e32 v234, s57, v1
	v_cmp_gt_i32_e32 vcc, s82, v234
	v_add_u32_e32 v168, 0xffff8000, v234
	v_readlane_b32 s2, v242, 47
	v_cndmask_b32_e32 v130, v168, v234, vcc
	v_lshl_or_b32 v154, s65, 8, v156
	v_ashrrev_i32_e32 v131, 31, v130
	v_readlane_b32 s3, v242, 48
	v_ashrrev_i32_e32 v155, 31, v154
	v_mov_b32_e32 v160, s39
	v_mov_b32_e32 v161, s37
	v_mov_b32_e32 v162, s38
	v_mov_b32_e32 v163, s36
	v_lshlrev_b64 v[130:131], 10, v[130:131]
	v_mov_b32_e32 v164, s81
	v_mov_b32_e32 v165, s3
	v_mov_b32_e32 v166, s80
	v_mov_b32_e32 v167, s2
	s_ashr_i32 s0, s57, 11
	v_cndmask_b32_e32 v133, v160, v161, vcc
	v_cndmask_b32_e32 v132, v162, v163, vcc
	v_lshl_add_u64 v[130:131], v[130:131], 0, v[154:155]
	v_cndmask_b32_e32 v201, v164, v165, vcc
	v_cndmask_b32_e32 v200, v166, v167, vcc
	v_lshrrev_b32_e32 v168, 3, v168
	v_lshl_add_u64 v[132:133], v[130:131], 2, v[132:133]
	v_add_u32_e32 v168, 16, v168
	v_mov_b32_e32 v235, s0
	v_lshl_add_u64 v[228:229], v[130:131], 1, v[200:201]
	v_or_b32_e32 v130, 16, v234
	v_cndmask_b32_e32 v168, v168, v235, vcc
	v_cmp_gt_i32_e32 vcc, s82, v130
	v_add_u32_e32 v200, 0xffff8010, v234
	v_lshl_add_u64 v[152:153], v[154:155], 2, s[50:51]
	v_cndmask_b32_e32 v130, v200, v130, vcc
	v_ashrrev_i32_e32 v131, 31, v130
	v_mad_i64_i32 v[196:197], s[0:1], v168, s78, v[152:153]
	v_lshlrev_b64 v[130:131], 10, v[130:131]
	global_load_dwordx4 v[168:171], v[132:133], off nt
	global_load_dwordx4 v[172:175], v[196:197], off
	global_load_dwordx4 v[176:179], v[132:133], off offset:64 nt
	global_load_dwordx4 v[180:183], v[196:197], off offset:64
	global_load_dwordx4 v[184:187], v[132:133], off offset:512 nt
	global_load_dwordx4 v[188:191], v[196:197], off offset:512
	global_load_dwordx4 v[192:195], v[132:133], off offset:576 nt
	s_nop 0
	global_load_dwordx4 v[196:199], v[196:197], off offset:576
	v_cndmask_b32_e32 v133, v160, v161, vcc
	v_cndmask_b32_e32 v132, v162, v163, vcc
	v_lshl_add_u64 v[230:231], v[130:131], 0, v[154:155]
	v_lshl_add_u64 v[130:131], v[230:231], 2, v[132:133]
	v_lshrrev_b32_e32 v132, 3, v200
	v_add_u32_e32 v132, 16, v132
	v_cndmask_b32_e32 v132, v132, v235, vcc
	v_mad_i64_i32 v[224:225], s[0:1], v132, s78, v[152:153]
	global_load_dwordx4 v[200:203], v[130:131], off nt
	global_load_dwordx4 v[204:207], v[224:225], off
	global_load_dwordx4 v[208:211], v[130:131], off offset:64 nt
	global_load_dwordx4 v[212:215], v[224:225], off offset:64
	global_load_dwordx4 v[216:219], v[130:131], off offset:512 nt
	global_load_dwordx4 v[220:223], v[224:225], off offset:512
	s_nop 0
	global_load_dwordx4 v[130:133], v[130:131], off offset:576 nt
	s_nop 0
	global_load_dwordx4 v[224:227], v[224:225], off offset:576
	v_cndmask_b32_e32 v233, v164, v165, vcc
	v_cndmask_b32_e32 v232, v166, v167, vcc
	v_lshl_add_u64 v[230:231], v[230:231], 1, v[232:233]
	s_addk_i32 s57, 0x80
	s_mov_b64 s[64:65], -1
	v_readlane_b32 s88, v242, 61
	v_readlane_b32 s89, v242, 62
	s_waitcnt vmcnt(0)
	v_pk_fma_f32 v[126:127], v[126:127], v[172:173], v[168:169]
	v_pk_fma_f32 v[128:129], v[128:129], v[174:175], v[170:171]
	v_pk_fma_f32 v[122:123], v[122:123], v[180:181], v[176:177]
	v_cvt_pk_bf16_f32 v126, v126, v127
	v_pk_fma_f32 v[118:119], v[118:119], v[188:189], v[184:185]
	v_cvt_pk_bf16_f32 v127, v128, v129
	v_pk_fma_f32 v[112:113], v[112:113], v[198:199], v[194:195]
	v_pk_fma_f32 v[110:111], v[110:111], v[196:197], v[192:193]
	global_store_dwordx2 v[228:229], v[126:127], off
	v_pk_fma_f32 v[124:125], v[124:125], v[182:183], v[178:179]
	v_cvt_pk_bf16_f32 v122, v122, v123
	v_pk_fma_f32 v[120:121], v[120:121], v[190:191], v[186:187]
	v_cvt_pk_bf16_f32 v123, v124, v125
	global_store_dwordx2 v[228:229], v[122:123], off offset:32
	v_cvt_pk_bf16_f32 v118, v118, v119
	v_cvt_pk_bf16_f32 v119, v120, v121
	global_store_dwordx2 v[228:229], v[118:119], off offset:256
	v_cvt_pk_bf16_f32 v110, v110, v111
	v_cvt_pk_bf16_f32 v111, v112, v113
	v_pk_fma_f32 v[112:113], v[114:115], v[204:205], v[200:201]
	v_pk_fma_f32 v[106:107], v[106:107], v[212:213], v[208:209]
	v_pk_fma_f32 v[102:103], v[102:103], v[220:221], v[216:217]
	v_pk_fma_f32 v[98:99], v[98:99], v[224:225], v[130:131]
	global_store_dwordx2 v[228:229], v[110:111], off offset:288
	v_pk_fma_f32 v[110:111], v[116:117], v[206:207], v[202:203]
	v_cvt_pk_bf16_f32 v112, v112, v113
	v_pk_fma_f32 v[108:109], v[108:109], v[214:215], v[210:211]
	v_cvt_pk_bf16_f32 v113, v110, v111
	global_store_dwordx2 v[230:231], v[112:113], off
	v_cvt_pk_bf16_f32 v106, v106, v107
	v_cvt_pk_bf16_f32 v107, v108, v109
	global_store_dwordx2 v[230:231], v[106:107], off offset:32
	v_pk_fma_f32 v[104:105], v[104:105], v[222:223], v[218:219]
	v_cvt_pk_bf16_f32 v102, v102, v103
	v_pk_fma_f32 v[100:101], v[100:101], v[226:227], v[132:133]
	v_cvt_pk_bf16_f32 v103, v104, v105
	global_store_dwordx2 v[230:231], v[102:103], off offset:256
	v_cvt_pk_bf16_f32 v98, v98, v99
	v_cvt_pk_bf16_f32 v99, v100, v101
	global_store_dwordx2 v[230:231], v[98:99], off offset:288
	v_or_b32_e32 v98, 32, v234
	v_cmp_gt_i32_e32 vcc, s82, v98
	v_add_u32_e32 v102, 0xffff8020, v234
	v_add_u32_e32 v168, 0xffff8030, v234
	v_cndmask_b32_e32 v98, v102, v98, vcc
	v_ashrrev_i32_e32 v99, 31, v98
	v_lshlrev_b64 v[98:99], 10, v[98:99]
	v_cndmask_b32_e32 v101, v160, v161, vcc
	v_cndmask_b32_e32 v100, v162, v163, vcc
	v_lshl_add_u64 v[130:131], v[98:99], 0, v[154:155]
	v_cndmask_b32_e32 v133, v164, v165, vcc
	v_cndmask_b32_e32 v132, v166, v167, vcc
	v_lshrrev_b32_e32 v98, 3, v102
	v_lshl_add_u64 v[122:123], v[130:131], 2, v[100:101]
	v_add_u32_e32 v98, 16, v98
	v_lshl_add_u64 v[196:197], v[130:131], 1, v[132:133]
	v_or_b32_e32 v130, 48, v234
	v_cndmask_b32_e32 v98, v98, v235, vcc
	v_cmp_gt_i32_e32 vcc, s82, v130
	v_mad_i64_i32 v[126:127], s[0:1], v98, s78, v[152:153]
	s_nop 0
	v_cndmask_b32_e32 v130, v168, v130, vcc
	v_ashrrev_i32_e32 v131, 31, v130
	v_lshlrev_b64 v[130:131], 10, v[130:131]
	v_lshl_add_u64 v[198:199], v[130:131], 0, v[154:155]
	v_lshrrev_b32_e32 v130, 3, v168
	v_add_u32_e32 v130, 16, v130
	global_load_dwordx4 v[98:101], v[122:123], off nt
	global_load_dwordx4 v[102:105], v[126:127], off
	global_load_dwordx4 v[106:109], v[122:123], off offset:64 nt
	global_load_dwordx4 v[110:113], v[126:127], off offset:64
	global_load_dwordx4 v[114:117], v[122:123], off offset:512 nt
	global_load_dwordx4 v[118:121], v[126:127], off offset:512
	s_nop 0
	global_load_dwordx4 v[122:125], v[122:123], off offset:576 nt
	s_nop 0
	global_load_dwordx4 v[126:129], v[126:127], off offset:576
	v_cndmask_b32_e32 v133, v160, v161, vcc
	v_cndmask_b32_e32 v132, v162, v163, vcc
	v_cndmask_b32_e32 v130, v130, v235, vcc
	v_lshl_add_u64 v[188:189], v[198:199], 2, v[132:133]
	v_mad_i64_i32 v[192:193], s[0:1], v130, s78, v[152:153]
	global_load_dwordx4 v[130:133], v[188:189], off nt
	global_load_dwordx4 v[168:171], v[192:193], off
	global_load_dwordx4 v[172:175], v[188:189], off offset:64 nt
	global_load_dwordx4 v[176:179], v[192:193], off offset:64
	global_load_dwordx4 v[180:183], v[188:189], off offset:512 nt
	global_load_dwordx4 v[184:187], v[192:193], off offset:512
	s_nop 0
	global_load_dwordx4 v[188:191], v[188:189], off offset:576 nt
	s_nop 0
	global_load_dwordx4 v[192:195], v[192:193], off offset:576
	v_cndmask_b32_e32 v201, v164, v165, vcc
	v_cndmask_b32_e32 v200, v166, v167, vcc
	v_lshl_add_u64 v[198:199], v[198:199], 1, v[200:201]
	s_ashr_i32 s0, s57, 11
	s_waitcnt vmcnt(14)
	v_pk_fma_f32 v[94:95], v[94:95], v[102:103], v[98:99]
	v_pk_fma_f32 v[96:97], v[96:97], v[104:105], v[100:101]
	s_waitcnt vmcnt(12)
	v_pk_fma_f32 v[90:91], v[90:91], v[110:111], v[106:107]
	v_cvt_pk_bf16_f32 v94, v94, v95
	s_waitcnt vmcnt(10)
	v_pk_fma_f32 v[86:87], v[86:87], v[118:119], v[114:115]
	v_cvt_pk_bf16_f32 v95, v96, v97
	s_waitcnt vmcnt(8)
	v_pk_fma_f32 v[80:81], v[80:81], v[128:129], v[124:125]
	v_pk_fma_f32 v[78:79], v[78:79], v[126:127], v[122:123]
	global_store_dwordx2 v[196:197], v[94:95], off
	v_pk_fma_f32 v[92:93], v[92:93], v[112:113], v[108:109]
	v_cvt_pk_bf16_f32 v90, v90, v91
	v_pk_fma_f32 v[88:89], v[88:89], v[120:121], v[116:117]
	v_cvt_pk_bf16_f32 v91, v92, v93
	global_store_dwordx2 v[196:197], v[90:91], off offset:32
	v_cvt_pk_bf16_f32 v86, v86, v87
	v_cvt_pk_bf16_f32 v87, v88, v89
	global_store_dwordx2 v[196:197], v[86:87], off offset:256
	v_cvt_pk_bf16_f32 v78, v78, v79
	v_cvt_pk_bf16_f32 v79, v80, v81
	s_waitcnt vmcnt(9)
	v_pk_fma_f32 v[80:81], v[82:83], v[168:169], v[130:131]
	s_waitcnt vmcnt(7)
	v_pk_fma_f32 v[74:75], v[74:75], v[176:177], v[172:173]
	s_waitcnt vmcnt(5)
	v_pk_fma_f32 v[70:71], v[70:71], v[184:185], v[180:181]
	global_store_dwordx2 v[196:197], v[78:79], off offset:288
	v_pk_fma_f32 v[78:79], v[84:85], v[170:171], v[132:133]
	v_cvt_pk_bf16_f32 v80, v80, v81
	v_pk_fma_f32 v[76:77], v[76:77], v[178:179], v[174:175]
	v_cvt_pk_bf16_f32 v81, v78, v79
	global_store_dwordx2 v[198:199], v[80:81], off
	v_cvt_pk_bf16_f32 v74, v74, v75
	v_cvt_pk_bf16_f32 v75, v76, v77
	global_store_dwordx2 v[198:199], v[74:75], off offset:32
	v_cvt_pk_bf16_f32 v70, v70, v71
	s_waitcnt vmcnt(6)
	v_pk_fma_f32 v[66:67], v[66:67], v[192:193], v[188:189]
	v_or_b32_e32 v170, s57, v1
	v_pk_fma_f32 v[72:73], v[72:73], v[186:187], v[182:183]
	v_cmp_gt_i32_e32 vcc, s82, v170
	v_cvt_pk_bf16_f32 v71, v72, v73
	global_store_dwordx2 v[198:199], v[70:71], off offset:256
	v_cvt_pk_bf16_f32 v66, v66, v67
	v_add_u32_e32 v70, 0xffff8000, v170
	v_pk_fma_f32 v[68:69], v[68:69], v[194:195], v[190:191]
	v_cndmask_b32_e32 v101, v164, v165, vcc
	v_cvt_pk_bf16_f32 v67, v68, v69
	global_store_dwordx2 v[198:199], v[66:67], off offset:288
	v_cndmask_b32_e32 v66, v70, v170, vcc
	v_ashrrev_i32_e32 v67, 31, v66
	v_lshlrev_b64 v[66:67], 10, v[66:67]
	v_cndmask_b32_e32 v69, v160, v161, vcc
	v_cndmask_b32_e32 v68, v162, v163, vcc
	v_lshl_add_u64 v[98:99], v[66:67], 0, v[154:155]
	v_cndmask_b32_e32 v100, v166, v167, vcc
	v_lshrrev_b32_e32 v66, 3, v70
	v_lshl_add_u64 v[90:91], v[98:99], 2, v[68:69]
	v_add_u32_e32 v66, 16, v66
	v_mov_b32_e32 v171, s0
	v_lshl_add_u64 v[130:131], v[98:99], 1, v[100:101]
	v_or_b32_e32 v98, 16, v170
	v_cndmask_b32_e32 v66, v66, v171, vcc
	v_cmp_gt_i32_e32 vcc, s82, v98
	v_add_u32_e32 v102, 0xffff8010, v170
	v_mad_i64_i32 v[94:95], s[0:1], v66, s78, v[152:153]
	v_cndmask_b32_e32 v98, v102, v98, vcc
	v_ashrrev_i32_e32 v99, 31, v98
	v_lshlrev_b64 v[98:99], 10, v[98:99]
	v_lshl_add_u64 v[132:133], v[98:99], 0, v[154:155]
	v_lshrrev_b32_e32 v98, 3, v102
	v_add_u32_e32 v98, 16, v98
	v_cndmask_b32_e32 v101, v160, v161, vcc
	v_cndmask_b32_e32 v100, v162, v163, vcc
	v_cndmask_b32_e32 v98, v98, v171, vcc
	v_lshl_add_u64 v[122:123], v[132:133], 2, v[100:101]
	v_mad_i64_i32 v[126:127], s[0:1], v98, s78, v[152:153]
	global_load_dwordx4 v[66:69], v[90:91], off nt
	global_load_dwordx4 v[70:73], v[94:95], off
	global_load_dwordx4 v[74:77], v[90:91], off offset:64 nt
	global_load_dwordx4 v[78:81], v[94:95], off offset:64
	global_load_dwordx4 v[82:85], v[90:91], off offset:512 nt
	global_load_dwordx4 v[86:89], v[94:95], off offset:512
	s_nop 0
	global_load_dwordx4 v[90:93], v[90:91], off offset:576 nt
	s_nop 0
	global_load_dwordx4 v[94:97], v[94:95], off offset:576
	s_nop 0
	global_load_dwordx4 v[98:101], v[122:123], off nt
	global_load_dwordx4 v[102:105], v[126:127], off
	global_load_dwordx4 v[106:109], v[122:123], off offset:64 nt
	global_load_dwordx4 v[110:113], v[126:127], off offset:64
	global_load_dwordx4 v[114:117], v[122:123], off offset:512 nt
	global_load_dwordx4 v[118:121], v[126:127], off offset:512
	s_nop 0
	global_load_dwordx4 v[122:125], v[122:123], off offset:576 nt
	s_nop 0
	global_load_dwordx4 v[126:129], v[126:127], off offset:576
	v_cndmask_b32_e32 v169, v164, v165, vcc
	v_cndmask_b32_e32 v168, v166, v167, vcc
	v_lshl_add_u64 v[132:133], v[132:133], 1, v[168:169]
	s_waitcnt vmcnt(14)
	v_pk_fma_f32 v[62:63], v[62:63], v[70:71], v[66:67]
	s_waitcnt vmcnt(6)
	v_pk_fma_f32 v[46:47], v[46:47], v[102:103], v[98:99]
	v_pk_fma_f32 v[58:59], v[58:59], v[78:79], v[74:75]
	s_waitcnt vmcnt(4)
	v_pk_fma_f32 v[42:43], v[42:43], v[110:111], v[106:107]
	v_pk_fma_f32 v[54:55], v[54:55], v[86:87], v[82:83]
	s_waitcnt vmcnt(2)
	v_pk_fma_f32 v[38:39], v[38:39], v[118:119], v[114:115]
	v_pk_fma_f32 v[50:51], v[50:51], v[94:95], v[90:91]
	s_waitcnt vmcnt(0)
	v_pk_fma_f32 v[34:35], v[34:35], v[126:127], v[122:123]
	v_pk_fma_f32 v[64:65], v[64:65], v[72:73], v[68:69]
	v_cvt_pk_bf16_f32 v62, v62, v63
	v_pk_fma_f32 v[60:61], v[60:61], v[80:81], v[76:77]
	v_cvt_pk_bf16_f32 v63, v64, v65
	global_store_dwordx2 v[130:131], v[62:63], off
	v_cvt_pk_bf16_f32 v58, v58, v59
	v_cvt_pk_bf16_f32 v59, v60, v61
	global_store_dwordx2 v[130:131], v[58:59], off offset:32
	v_pk_fma_f32 v[56:57], v[56:57], v[88:89], v[84:85]
	v_cvt_pk_bf16_f32 v54, v54, v55
	v_pk_fma_f32 v[52:53], v[52:53], v[96:97], v[92:93]
	v_cvt_pk_bf16_f32 v55, v56, v57
	global_store_dwordx2 v[130:131], v[54:55], off offset:256
	v_cvt_pk_bf16_f32 v50, v50, v51
	v_cvt_pk_bf16_f32 v51, v52, v53
	global_store_dwordx2 v[130:131], v[50:51], off offset:288
	v_pk_fma_f32 v[48:49], v[48:49], v[104:105], v[100:101]
	v_cvt_pk_bf16_f32 v46, v46, v47
	v_pk_fma_f32 v[44:45], v[44:45], v[112:113], v[108:109]
	v_cvt_pk_bf16_f32 v47, v48, v49
	global_store_dwordx2 v[132:133], v[46:47], off
	v_cvt_pk_bf16_f32 v42, v42, v43
	v_cvt_pk_bf16_f32 v43, v44, v45
	global_store_dwordx2 v[132:133], v[42:43], off offset:32
	v_pk_fma_f32 v[40:41], v[40:41], v[120:121], v[116:117]
	v_cvt_pk_bf16_f32 v38, v38, v39
	v_pk_fma_f32 v[36:37], v[36:37], v[128:129], v[124:125]
	v_cvt_pk_bf16_f32 v39, v40, v41
	global_store_dwordx2 v[132:133], v[38:39], off offset:256
	v_cvt_pk_bf16_f32 v34, v34, v35
	v_cvt_pk_bf16_f32 v35, v36, v37
	global_store_dwordx2 v[132:133], v[34:35], off offset:288
	v_or_b32_e32 v34, 32, v170
	v_cmp_gt_i32_e32 vcc, s82, v34
	v_add_u32_e32 v38, 0xffff8020, v170
	v_add_u32_e32 v70, 0xffff8030, v170
	v_cndmask_b32_e32 v34, v38, v34, vcc
	v_ashrrev_i32_e32 v35, 31, v34
	v_lshlrev_b64 v[34:35], 10, v[34:35]
	v_cndmask_b32_e32 v37, v160, v161, vcc
	v_cndmask_b32_e32 v36, v162, v163, vcc
	v_lshl_add_u64 v[66:67], v[34:35], 0, v[154:155]
	v_cndmask_b32_e32 v69, v164, v165, vcc
	v_cndmask_b32_e32 v68, v166, v167, vcc
	v_lshrrev_b32_e32 v34, 3, v38
	v_lshl_add_u64 v[58:59], v[66:67], 2, v[36:37]
	v_add_u32_e32 v34, 16, v34
	v_lshl_add_u64 v[98:99], v[66:67], 1, v[68:69]
	v_or_b32_e32 v66, 48, v170
	v_cndmask_b32_e32 v34, v34, v171, vcc
	v_cmp_gt_i32_e32 vcc, s82, v66
	v_mad_i64_i32 v[62:63], s[0:1], v34, s78, v[152:153]
	s_nop 0
	v_cndmask_b32_e32 v66, v70, v66, vcc
	v_ashrrev_i32_e32 v67, 31, v66
	v_lshlrev_b64 v[66:67], 10, v[66:67]
	v_lshl_add_u64 v[100:101], v[66:67], 0, v[154:155]
	v_lshrrev_b32_e32 v66, 3, v70
	v_add_u32_e32 v66, 16, v66
	v_cndmask_b32_e32 v69, v160, v161, vcc
	v_cndmask_b32_e32 v68, v162, v163, vcc
	v_cndmask_b32_e32 v66, v66, v171, vcc
	v_lshl_add_u64 v[90:91], v[100:101], 2, v[68:69]
	v_mad_i64_i32 v[94:95], s[0:1], v66, s78, v[152:153]
	global_load_dwordx4 v[34:37], v[58:59], off nt
	global_load_dwordx4 v[38:41], v[62:63], off
	global_load_dwordx4 v[42:45], v[58:59], off offset:64 nt
	global_load_dwordx4 v[46:49], v[62:63], off offset:64
	global_load_dwordx4 v[50:53], v[58:59], off offset:512 nt
	global_load_dwordx4 v[54:57], v[62:63], off offset:512
	s_nop 0
	global_load_dwordx4 v[58:61], v[58:59], off offset:576 nt
	s_nop 0
	global_load_dwordx4 v[62:65], v[62:63], off offset:576
	s_nop 0
	global_load_dwordx4 v[66:69], v[90:91], off nt
	global_load_dwordx4 v[70:73], v[94:95], off
	global_load_dwordx4 v[74:77], v[90:91], off offset:64 nt
	global_load_dwordx4 v[78:81], v[94:95], off offset:64
	global_load_dwordx4 v[82:85], v[90:91], off offset:512 nt
	global_load_dwordx4 v[86:89], v[94:95], off offset:512
	s_nop 0
	global_load_dwordx4 v[90:93], v[90:91], off offset:576 nt
	s_nop 0
	global_load_dwordx4 v[94:97], v[94:95], off offset:576
	v_cndmask_b32_e32 v103, v164, v165, vcc
	v_cndmask_b32_e32 v102, v166, v167, vcc
	v_lshl_add_u64 v[100:101], v[100:101], 1, v[102:103]
	s_andn2_b64 vcc, exec, s[4:5]
	s_waitcnt vmcnt(14)
	v_pk_fma_f32 v[30:31], v[30:31], v[38:39], v[34:35]
	s_waitcnt vmcnt(6)
	v_pk_fma_f32 v[14:15], v[14:15], v[70:71], v[66:67]
	v_pk_fma_f32 v[26:27], v[26:27], v[46:47], v[42:43]
	s_waitcnt vmcnt(4)
	v_pk_fma_f32 v[10:11], v[10:11], v[78:79], v[74:75]
	v_pk_fma_f32 v[22:23], v[22:23], v[54:55], v[50:51]
	s_waitcnt vmcnt(2)
	v_pk_fma_f32 v[6:7], v[6:7], v[86:87], v[82:83]
	v_pk_fma_f32 v[18:19], v[18:19], v[62:63], v[58:59]
	s_waitcnt vmcnt(0)
	v_pk_fma_f32 v[2:3], v[2:3], v[94:95], v[90:91]
	v_pk_fma_f32 v[32:33], v[32:33], v[40:41], v[36:37]
	v_cvt_pk_bf16_f32 v30, v30, v31
	v_pk_fma_f32 v[28:29], v[28:29], v[48:49], v[44:45]
	v_cvt_pk_bf16_f32 v31, v32, v33
	global_store_dwordx2 v[98:99], v[30:31], off
	v_cvt_pk_bf16_f32 v26, v26, v27
	v_cvt_pk_bf16_f32 v27, v28, v29
	global_store_dwordx2 v[98:99], v[26:27], off offset:32
	v_pk_fma_f32 v[24:25], v[24:25], v[56:57], v[52:53]
	v_cvt_pk_bf16_f32 v22, v22, v23
	v_pk_fma_f32 v[20:21], v[20:21], v[64:65], v[60:61]
	v_cvt_pk_bf16_f32 v23, v24, v25
	global_store_dwordx2 v[98:99], v[22:23], off offset:256
	v_cvt_pk_bf16_f32 v18, v18, v19
	v_cvt_pk_bf16_f32 v19, v20, v21
	global_store_dwordx2 v[98:99], v[18:19], off offset:288
	v_pk_fma_f32 v[16:17], v[16:17], v[72:73], v[68:69]
	v_cvt_pk_bf16_f32 v14, v14, v15
	v_pk_fma_f32 v[12:13], v[12:13], v[80:81], v[76:77]
	v_cvt_pk_bf16_f32 v15, v16, v17
	global_store_dwordx2 v[100:101], v[14:15], off
	v_cvt_pk_bf16_f32 v10, v10, v11
	v_cvt_pk_bf16_f32 v11, v12, v13
	global_store_dwordx2 v[100:101], v[10:11], off offset:32
	v_pk_fma_f32 v[8:9], v[8:9], v[88:89], v[84:85]
	v_cvt_pk_bf16_f32 v6, v6, v7
	v_pk_fma_f32 v[4:5], v[4:5], v[96:97], v[92:93]
	v_cvt_pk_bf16_f32 v7, v8, v9
	global_store_dwordx2 v[100:101], v[6:7], off offset:256
	v_cvt_pk_bf16_f32 v2, v2, v3
	v_cvt_pk_bf16_f32 v3, v4, v5
	global_store_dwordx2 v[100:101], v[2:3], off offset:288
	s_cbranch_vccnz .LBB0_1793
	s_andn2_b64 vcc, exec, s[48:49]
	s_cbranch_vccnz .LBB0_1792
	s_barrier
	s_branch .LBB0_1792

.LBB0_2144:
	s_lshl_b32 s8, s8, 8
	s_add_i32 s8, s8, s39
	v_or_b32_e32 v222, s8, v146
	v_add_u32_e32 v160, 0xffff8000, v222
	v_cmp_gt_i32_e32 vcc, s51, v222
	v_readlane_b32 s0, v242, 47
	v_lshl_or_b32 v142, s54, 8, v150
	v_cndmask_b32_e32 v144, v160, v222, vcc
	v_readlane_b32 s1, v242, 48
	v_ashrrev_i32_e32 v145, 31, v144
	v_ashrrev_i32_e32 v143, 31, v142
	v_mov_b32_e32 v154, s41
	v_mov_b32_e32 v155, s1
	v_mov_b32_e32 v156, s40
	v_mov_b32_e32 v157, s0
	v_lshlrev_b64 v[144:145], 10, v[144:145]
	s_ashr_i32 s0, s8, 11
	v_lshrrev_b32_e32 v160, 3, v160
	v_cndmask_b32_e32 v159, v154, v155, vcc
	v_cndmask_b32_e32 v158, v156, v157, vcc
	v_lshl_add_u64 v[194:195], v[144:145], 0, v[142:143]
	v_add_u32_e32 v160, 16, v160
	v_mov_b32_e32 v223, s0
	v_lshl_add_u64 v[158:159], v[194:195], 1, v[158:159]
	v_lshl_add_u64 v[144:145], v[142:143], 2, s[12:13]
	v_cndmask_b32_e32 v160, v160, v223, vcc
	global_load_dwordx2 v[196:197], v[158:159], off nt
	global_load_dwordx2 v[198:199], v[158:159], off offset:32 nt
	global_load_dwordx2 v[200:201], v[158:159], off offset:256 nt
	v_mad_i64_i32 v[160:161], s[0:1], v160, s38, v[144:145]
	global_load_dwordx2 v[202:203], v[158:159], off offset:288 nt
	global_load_dwordx4 v[162:165], v[160:161], off
	global_load_dwordx4 v[166:169], v[160:161], off offset:64
	global_load_dwordx4 v[170:173], v[160:161], off offset:512
	global_load_dwordx4 v[174:177], v[160:161], off offset:576
	v_or_b32_e32 v158, 16, v222
	v_add_u32_e32 v178, 0xffff8010, v222
	v_cmp_gt_i32_e64 s[6:7], s51, v158
	v_readlane_b32 s56, v242, 2
	v_readlane_b32 s57, v242, 3
	v_cndmask_b32_e64 v158, v178, v158, s[6:7]
	v_ashrrev_i32_e32 v159, 31, v158
	v_lshlrev_b64 v[158:159], 10, v[158:159]
	v_cndmask_b32_e64 v161, v154, v155, s[6:7]
	v_cndmask_b32_e64 v160, v156, v157, s[6:7]
	v_lshl_add_u64 v[204:205], v[158:159], 0, v[142:143]
	v_lshl_add_u64 v[158:159], v[204:205], 1, v[160:161]
	global_load_dwordx2 v[206:207], v[158:159], off nt
	v_lshrrev_b32_e32 v160, 3, v178
	v_add_u32_e32 v160, 16, v160
	v_cndmask_b32_e64 v160, v160, v223, s[6:7]
	v_mad_i64_i32 v[160:161], s[0:1], v160, s38, v[144:145]
	global_load_dwordx4 v[178:181], v[160:161], off
	global_load_dwordx2 v[208:209], v[158:159], off offset:32 nt
	global_load_dwordx4 v[182:185], v[160:161], off offset:64
	global_load_dwordx2 v[210:211], v[158:159], off offset:256 nt
	global_load_dwordx4 v[186:189], v[160:161], off offset:512
	global_load_dwordx2 v[212:213], v[158:159], off offset:288 nt
	global_load_dwordx4 v[190:193], v[160:161], off offset:576
	s_mov_b64 s[0:1], s[56:57]
	v_mov_b32_e32 v158, s43
	v_mov_b32_e32 v159, s1
	v_mov_b32_e32 v160, s42
	v_mov_b32_e32 v161, s0
	v_cndmask_b32_e32 v215, v158, v159, vcc
	v_cndmask_b32_e32 v214, v160, v161, vcc
	v_cndmask_b32_e64 v217, v158, v159, s[6:7]
	v_cndmask_b32_e64 v216, v160, v161, s[6:7]
	v_lshl_add_u64 v[194:195], v[194:195], 2, v[214:215]
	v_lshl_add_u64 v[204:205], v[204:205], 2, v[216:217]
	s_addk_i32 s8, 0x80
	v_readlane_b32 s58, v242, 4
	v_readlane_b32 s59, v242, 5
	s_waitcnt vmcnt(0)
	v_lshlrev_b32_e32 v214, 16, v196
	v_and_b32_e32 v215, 0xffff0000, v196
	v_lshlrev_b32_e32 v196, 16, v197
	v_and_b32_e32 v197, 0xffff0000, v197
	v_lshlrev_b32_e32 v220, 16, v202
	v_and_b32_e32 v221, 0xffff0000, v202
	v_lshlrev_b32_e32 v202, 16, v203
	v_and_b32_e32 v203, 0xffff0000, v203
	v_lshlrev_b32_e32 v216, 16, v198
	v_and_b32_e32 v217, 0xffff0000, v198
	v_lshlrev_b32_e32 v198, 16, v199
	v_and_b32_e32 v199, 0xffff0000, v199
	v_lshlrev_b32_e32 v218, 16, v200
	v_and_b32_e32 v219, 0xffff0000, v200
	v_lshlrev_b32_e32 v200, 16, v201
	v_and_b32_e32 v201, 0xffff0000, v201
	v_pk_fma_f32 v[126:127], v[126:127], v[164:165], v[196:197]
	v_pk_fma_f32 v[124:125], v[124:125], v[162:163], v[214:215]
	v_pk_fma_f32 v[110:111], v[110:111], v[176:177], v[202:203]
	v_pk_fma_f32 v[108:109], v[108:109], v[174:175], v[220:221]
	v_pk_fma_f32 v[122:123], v[122:123], v[168:169], v[198:199]
	v_pk_fma_f32 v[120:121], v[120:121], v[166:167], v[216:217]
	v_pk_fma_f32 v[118:119], v[118:119], v[172:173], v[200:201]
	v_pk_fma_f32 v[116:117], v[116:117], v[170:171], v[218:219]
	global_store_dwordx4 v[194:195], v[124:127], off nt
	global_store_dwordx4 v[194:195], v[120:123], off offset:64 nt
	global_store_dwordx4 v[194:195], v[116:119], off offset:512 nt
	global_store_dwordx4 v[194:195], v[108:111], off offset:576 nt
	s_nop 0
	v_add_u32_e32 v116, 0xffff8030, v222
	v_lshlrev_b32_e32 v108, 16, v206
	v_and_b32_e32 v109, 0xffff0000, v206
	v_lshlrev_b32_e32 v110, 16, v207
	v_and_b32_e32 v111, 0xffff0000, v207
	v_pk_fma_f32 v[110:111], v[114:115], v[180:181], v[110:111]
	v_pk_fma_f32 v[108:109], v[112:113], v[178:179], v[108:109]
	global_store_dwordx4 v[204:205], v[108:111], off nt
	v_or_b32_e32 v112, 48, v222
	v_cmp_gt_i32_e64 s[6:7], s51, v112
	v_lshlrev_b32_e32 v108, 16, v208
	v_and_b32_e32 v109, 0xffff0000, v208
	v_lshlrev_b32_e32 v110, 16, v209
	v_and_b32_e32 v111, 0xffff0000, v209
	v_pk_fma_f32 v[106:107], v[106:107], v[184:185], v[110:111]
	v_pk_fma_f32 v[104:105], v[104:105], v[182:183], v[108:109]
	global_store_dwordx4 v[204:205], v[104:107], off offset:64 nt
	v_cndmask_b32_e64 v112, v116, v112, s[6:7]
	v_ashrrev_i32_e32 v113, 31, v112
	v_lshlrev_b32_e32 v104, 16, v210
	v_and_b32_e32 v105, 0xffff0000, v210
	v_lshlrev_b32_e32 v106, 16, v211
	v_and_b32_e32 v107, 0xffff0000, v211
	v_pk_fma_f32 v[102:103], v[102:103], v[188:189], v[106:107]
	v_pk_fma_f32 v[100:101], v[100:101], v[186:187], v[104:105]
	global_store_dwordx4 v[204:205], v[100:103], off offset:512 nt
	v_lshlrev_b64 v[112:113], 10, v[112:113]
	v_cndmask_b32_e64 v115, v154, v155, s[6:7]
	v_lshlrev_b32_e32 v100, 16, v212
	v_and_b32_e32 v101, 0xffff0000, v212
	v_lshlrev_b32_e32 v102, 16, v213
	v_and_b32_e32 v103, 0xffff0000, v213
	v_pk_fma_f32 v[98:99], v[98:99], v[192:193], v[102:103]
	v_pk_fma_f32 v[96:97], v[96:97], v[190:191], v[100:101]
	global_store_dwordx4 v[204:205], v[96:99], off offset:576 nt
	v_add_u32_e32 v100, 0xffff8020, v222
	v_cndmask_b32_e64 v114, v156, v157, s[6:7]
	v_or_b32_e32 v96, 32, v222
	v_cmp_gt_i32_e32 vcc, s51, v96
	v_lshl_add_u64 v[172:173], v[112:113], 0, v[142:143]
	v_lshl_add_u64 v[124:125], v[172:173], 1, v[114:115]
	v_cndmask_b32_e32 v96, v100, v96, vcc
	v_ashrrev_i32_e32 v97, 31, v96
	v_lshlrev_b64 v[96:97], 10, v[96:97]
	v_cndmask_b32_e32 v99, v154, v155, vcc
	v_cndmask_b32_e32 v98, v156, v157, vcc
	v_lshl_add_u64 v[162:163], v[96:97], 0, v[142:143]
	v_lshl_add_u64 v[104:105], v[162:163], 1, v[98:99]
	global_load_dwordx2 v[164:165], v[104:105], off nt
	v_lshrrev_b32_e32 v96, 3, v100
	v_add_u32_e32 v96, 16, v96
	v_cndmask_b32_e32 v96, v96, v223, vcc
	v_mad_i64_i32 v[108:109], s[0:1], v96, s38, v[144:145]
	global_load_dwordx4 v[96:99], v[108:109], off
	global_load_dwordx2 v[166:167], v[104:105], off offset:32 nt
	global_load_dwordx4 v[100:103], v[108:109], off offset:64
	global_load_dwordx2 v[168:169], v[104:105], off offset:256 nt
	global_load_dwordx2 v[170:171], v[104:105], off offset:288 nt
	s_nop 0
	global_load_dwordx4 v[104:107], v[108:109], off offset:512
	s_nop 0
	global_load_dwordx4 v[108:111], v[108:109], off offset:576
	v_lshrrev_b32_e32 v112, 3, v116
	global_load_dwordx2 v[174:175], v[124:125], off nt
	v_add_u32_e32 v112, 16, v112
	v_cndmask_b32_e64 v112, v112, v223, s[6:7]
	v_mad_i64_i32 v[126:127], s[0:1], v112, s38, v[144:145]
	global_load_dwordx4 v[112:115], v[126:127], off
	global_load_dwordx2 v[176:177], v[124:125], off offset:32 nt
	global_load_dwordx4 v[116:119], v[126:127], off offset:64
	global_load_dwordx2 v[178:179], v[124:125], off offset:256 nt
	global_load_dwordx4 v[120:123], v[126:127], off offset:512
	global_load_dwordx2 v[180:181], v[124:125], off offset:288 nt
	s_nop 0
	global_load_dwordx4 v[124:127], v[126:127], off offset:576
	v_cndmask_b32_e32 v183, v158, v159, vcc
	v_cndmask_b32_e32 v182, v160, v161, vcc
	v_lshl_add_u64 v[162:163], v[162:163], 2, v[182:183]
	v_cndmask_b32_e64 v183, v158, v159, s[6:7]
	v_cndmask_b32_e64 v182, v160, v161, s[6:7]
	v_lshl_add_u64 v[172:173], v[172:173], 2, v[182:183]
	s_ashr_i32 s0, s8, 11
	s_waitcnt vmcnt(15)
	v_lshlrev_b32_e32 v182, 16, v164
	v_and_b32_e32 v183, 0xffff0000, v164
	v_lshlrev_b32_e32 v164, 16, v165
	v_and_b32_e32 v165, 0xffff0000, v165
	s_waitcnt vmcnt(14)
	v_pk_fma_f32 v[94:95], v[94:95], v[98:99], v[164:165]
	v_pk_fma_f32 v[92:93], v[92:93], v[96:97], v[182:183]
	global_store_dwordx4 v[162:163], v[92:95], off nt
	s_waitcnt vmcnt(14)
	s_nop 0
	v_lshlrev_b32_e32 v92, 16, v166
	v_and_b32_e32 v93, 0xffff0000, v166
	v_lshlrev_b32_e32 v94, 16, v167
	v_and_b32_e32 v95, 0xffff0000, v167
	s_waitcnt vmcnt(13)
	v_pk_fma_f32 v[90:91], v[90:91], v[102:103], v[94:95]
	v_pk_fma_f32 v[88:89], v[88:89], v[100:101], v[92:93]
	global_store_dwordx4 v[162:163], v[88:91], off offset:64 nt
	s_waitcnt vmcnt(13)
	s_nop 0
	v_lshlrev_b32_e32 v88, 16, v168
	v_and_b32_e32 v89, 0xffff0000, v168
	v_lshlrev_b32_e32 v90, 16, v169
	v_and_b32_e32 v91, 0xffff0000, v169
	s_waitcnt vmcnt(11)
	v_pk_fma_f32 v[86:87], v[86:87], v[106:107], v[90:91]
	v_pk_fma_f32 v[84:85], v[84:85], v[104:105], v[88:89]
	global_store_dwordx4 v[162:163], v[84:87], off offset:512 nt
	s_nop 1
	v_lshlrev_b32_e32 v84, 16, v170
	v_and_b32_e32 v85, 0xffff0000, v170
	v_lshlrev_b32_e32 v86, 16, v171
	v_and_b32_e32 v87, 0xffff0000, v171
	s_waitcnt vmcnt(11)
	v_pk_fma_f32 v[78:79], v[78:79], v[110:111], v[86:87]
	v_pk_fma_f32 v[76:77], v[76:77], v[108:109], v[84:85]
	global_store_dwordx4 v[162:163], v[76:79], off offset:576 nt
	s_waitcnt vmcnt(11)
	s_nop 0
	v_lshlrev_b32_e32 v76, 16, v174
	v_and_b32_e32 v77, 0xffff0000, v174
	v_lshlrev_b32_e32 v78, 16, v175
	v_and_b32_e32 v79, 0xffff0000, v175
	s_waitcnt vmcnt(10)
	v_pk_fma_f32 v[78:79], v[82:83], v[114:115], v[78:79]
	v_pk_fma_f32 v[76:77], v[80:81], v[112:113], v[76:77]
	global_store_dwordx4 v[172:173], v[76:79], off nt
	s_waitcnt vmcnt(10)
	s_nop 0
	v_lshlrev_b32_e32 v76, 16, v176
	v_and_b32_e32 v77, 0xffff0000, v176
	v_lshlrev_b32_e32 v78, 16, v177
	v_and_b32_e32 v79, 0xffff0000, v177
	s_waitcnt vmcnt(9)
	v_pk_fma_f32 v[74:75], v[74:75], v[118:119], v[78:79]
	v_pk_fma_f32 v[72:73], v[72:73], v[116:117], v[76:77]
	global_store_dwordx4 v[172:173], v[72:75], off offset:64 nt
	v_or_b32_e32 v118, s8, v146
	v_cmp_gt_i32_e32 vcc, s51, v118
	s_waitcnt vmcnt(9)
	v_lshlrev_b32_e32 v72, 16, v178
	v_and_b32_e32 v73, 0xffff0000, v178
	v_lshlrev_b32_e32 v74, 16, v179
	v_and_b32_e32 v75, 0xffff0000, v179
	s_waitcnt vmcnt(8)
	v_pk_fma_f32 v[70:71], v[70:71], v[122:123], v[74:75]
	v_pk_fma_f32 v[68:69], v[68:69], v[120:121], v[72:73]
	global_store_dwordx4 v[172:173], v[68:71], off offset:512 nt
	v_or_b32_e32 v80, 16, v118
	v_add_u32_e32 v84, 0xffff8010, v118
	s_waitcnt vmcnt(8)
	v_lshlrev_b32_e32 v68, 16, v180
	v_and_b32_e32 v69, 0xffff0000, v180
	v_lshlrev_b32_e32 v70, 16, v181
	v_and_b32_e32 v71, 0xffff0000, v181
	s_waitcnt vmcnt(7)
	v_pk_fma_f32 v[66:67], v[66:67], v[126:127], v[70:71]
	v_pk_fma_f32 v[64:65], v[64:65], v[124:125], v[68:69]
	v_add_u32_e32 v68, 0xffff8000, v118
	global_store_dwordx4 v[172:173], v[64:67], off offset:576 nt
	v_cmp_gt_i32_e64 s[6:7], s51, v80
	v_mov_b32_e32 v119, s0
	v_cndmask_b32_e32 v64, v68, v118, vcc
	v_ashrrev_i32_e32 v65, 31, v64
	v_lshlrev_b64 v[64:65], 10, v[64:65]
	v_cndmask_b32_e32 v67, v154, v155, vcc
	v_cndmask_b32_e32 v66, v156, v157, vcc
	v_lshl_add_u64 v[96:97], v[64:65], 0, v[142:143]
	v_lshl_add_u64 v[72:73], v[96:97], 1, v[66:67]
	global_load_dwordx2 v[98:99], v[72:73], off nt
	v_lshrrev_b32_e32 v64, 3, v68
	v_add_u32_e32 v64, 16, v64
	v_cndmask_b32_e64 v80, v84, v80, s[6:7]
	v_cndmask_b32_e32 v64, v64, v119, vcc
	v_ashrrev_i32_e32 v81, 31, v80
	v_mad_i64_i32 v[76:77], s[0:1], v64, s38, v[144:145]
	v_lshlrev_b64 v[80:81], 10, v[80:81]
	global_load_dwordx4 v[64:67], v[76:77], off
	global_load_dwordx2 v[100:101], v[72:73], off offset:32 nt
	global_load_dwordx4 v[68:71], v[76:77], off offset:64
	global_load_dwordx2 v[102:103], v[72:73], off offset:256 nt
	global_load_dwordx2 v[104:105], v[72:73], off offset:288 nt
	s_nop 0
	global_load_dwordx4 v[72:75], v[76:77], off offset:512
	s_nop 0
	global_load_dwordx4 v[76:79], v[76:77], off offset:576
	v_cndmask_b32_e64 v83, v154, v155, s[6:7]
	v_cndmask_b32_e64 v82, v156, v157, s[6:7]
	v_lshl_add_u64 v[106:107], v[80:81], 0, v[142:143]
	v_lshl_add_u64 v[92:93], v[106:107], 1, v[82:83]
	global_load_dwordx2 v[108:109], v[92:93], off nt
	v_lshrrev_b32_e32 v80, 3, v84
	v_add_u32_e32 v80, 16, v80
	v_cndmask_b32_e64 v80, v80, v119, s[6:7]
	v_mad_i64_i32 v[94:95], s[0:1], v80, s38, v[144:145]
	global_load_dwordx4 v[80:83], v[94:95], off
	global_load_dwordx2 v[110:111], v[92:93], off offset:32 nt
	global_load_dwordx4 v[84:87], v[94:95], off offset:64
	global_load_dwordx2 v[112:113], v[92:93], off offset:256 nt
	global_load_dwordx4 v[88:91], v[94:95], off offset:512
	global_load_dwordx2 v[114:115], v[92:93], off offset:288 nt
	s_nop 0
	global_load_dwordx4 v[92:95], v[94:95], off offset:576
	v_cndmask_b32_e32 v117, v158, v159, vcc
	v_cndmask_b32_e32 v116, v160, v161, vcc
	v_lshl_add_u64 v[96:97], v[96:97], 2, v[116:117]
	v_cndmask_b32_e64 v117, v158, v159, s[6:7]
	v_cndmask_b32_e64 v116, v160, v161, s[6:7]
	v_lshl_add_u64 v[106:107], v[106:107], 2, v[116:117]
	s_waitcnt vmcnt(15)
	v_lshlrev_b32_e32 v116, 16, v98
	v_and_b32_e32 v117, 0xffff0000, v98
	v_lshlrev_b32_e32 v98, 16, v99
	v_and_b32_e32 v99, 0xffff0000, v99
	s_waitcnt vmcnt(14)
	v_pk_fma_f32 v[62:63], v[62:63], v[66:67], v[98:99]
	v_pk_fma_f32 v[60:61], v[60:61], v[64:65], v[116:117]
	global_store_dwordx4 v[96:97], v[60:63], off nt
	s_waitcnt vmcnt(14)
	s_nop 0
	v_lshlrev_b32_e32 v60, 16, v100
	v_and_b32_e32 v61, 0xffff0000, v100
	v_lshlrev_b32_e32 v62, 16, v101
	v_and_b32_e32 v63, 0xffff0000, v101
	s_waitcnt vmcnt(13)
	v_pk_fma_f32 v[58:59], v[58:59], v[70:71], v[62:63]
	v_pk_fma_f32 v[56:57], v[56:57], v[68:69], v[60:61]
	global_store_dwordx4 v[96:97], v[56:59], off offset:64 nt
	s_waitcnt vmcnt(13)
	s_nop 0
	v_lshlrev_b32_e32 v56, 16, v102
	v_and_b32_e32 v57, 0xffff0000, v102
	v_lshlrev_b32_e32 v58, 16, v103
	v_and_b32_e32 v59, 0xffff0000, v103
	s_waitcnt vmcnt(11)
	v_pk_fma_f32 v[54:55], v[54:55], v[74:75], v[58:59]
	v_pk_fma_f32 v[52:53], v[52:53], v[72:73], v[56:57]
	global_store_dwordx4 v[96:97], v[52:55], off offset:512 nt
	s_nop 1
	v_lshlrev_b32_e32 v52, 16, v104
	v_and_b32_e32 v53, 0xffff0000, v104
	v_lshlrev_b32_e32 v54, 16, v105
	v_and_b32_e32 v55, 0xffff0000, v105
	s_waitcnt vmcnt(11)
	v_pk_fma_f32 v[46:47], v[46:47], v[78:79], v[54:55]
	v_pk_fma_f32 v[44:45], v[44:45], v[76:77], v[52:53]
	global_store_dwordx4 v[96:97], v[44:47], off offset:576 nt
	v_add_u32_e32 v52, 0xffff8030, v118
	s_waitcnt vmcnt(11)
	v_lshlrev_b32_e32 v44, 16, v108
	v_and_b32_e32 v45, 0xffff0000, v108
	v_lshlrev_b32_e32 v46, 16, v109
	v_and_b32_e32 v47, 0xffff0000, v109
	s_waitcnt vmcnt(10)
	v_pk_fma_f32 v[46:47], v[50:51], v[82:83], v[46:47]
	v_pk_fma_f32 v[44:45], v[48:49], v[80:81], v[44:45]
	global_store_dwordx4 v[106:107], v[44:47], off nt
	v_or_b32_e32 v48, 48, v118
	v_cmp_gt_i32_e64 s[6:7], s51, v48
	s_waitcnt vmcnt(10)
	v_lshlrev_b32_e32 v44, 16, v110
	v_and_b32_e32 v45, 0xffff0000, v110
	v_lshlrev_b32_e32 v46, 16, v111
	v_and_b32_e32 v47, 0xffff0000, v111
	s_waitcnt vmcnt(9)
	v_pk_fma_f32 v[42:43], v[42:43], v[86:87], v[46:47]
	v_pk_fma_f32 v[40:41], v[40:41], v[84:85], v[44:45]
	global_store_dwordx4 v[106:107], v[40:43], off offset:64 nt
	v_cndmask_b32_e64 v48, v52, v48, s[6:7]
	v_ashrrev_i32_e32 v49, 31, v48
	s_waitcnt vmcnt(9)
	v_lshlrev_b32_e32 v40, 16, v112
	v_and_b32_e32 v41, 0xffff0000, v112
	v_lshlrev_b32_e32 v42, 16, v113
	v_and_b32_e32 v43, 0xffff0000, v113
	s_waitcnt vmcnt(8)
	v_pk_fma_f32 v[38:39], v[38:39], v[90:91], v[42:43]
	v_pk_fma_f32 v[36:37], v[36:37], v[88:89], v[40:41]
	global_store_dwordx4 v[106:107], v[36:39], off offset:512 nt
	v_lshlrev_b64 v[48:49], 10, v[48:49]
	v_cndmask_b32_e64 v51, v154, v155, s[6:7]
	s_waitcnt vmcnt(8)
	v_lshlrev_b32_e32 v36, 16, v114
	v_and_b32_e32 v37, 0xffff0000, v114
	v_lshlrev_b32_e32 v38, 16, v115
	v_and_b32_e32 v39, 0xffff0000, v115
	s_waitcnt vmcnt(7)
	v_pk_fma_f32 v[34:35], v[34:35], v[94:95], v[38:39]
	v_pk_fma_f32 v[32:33], v[32:33], v[92:93], v[36:37]
	global_store_dwordx4 v[106:107], v[32:35], off offset:576 nt
	v_add_u32_e32 v36, 0xffff8020, v118
	v_cndmask_b32_e64 v50, v156, v157, s[6:7]
	v_or_b32_e32 v32, 32, v118
	v_cmp_gt_i32_e32 vcc, s51, v32
	v_lshl_add_u64 v[74:75], v[48:49], 0, v[142:143]
	v_lshl_add_u64 v[60:61], v[74:75], 1, v[50:51]
	v_cndmask_b32_e32 v32, v36, v32, vcc
	v_ashrrev_i32_e32 v33, 31, v32
	v_lshlrev_b64 v[32:33], 10, v[32:33]
	v_cndmask_b32_e32 v35, v154, v155, vcc
	v_cndmask_b32_e32 v34, v156, v157, vcc
	v_lshl_add_u64 v[64:65], v[32:33], 0, v[142:143]
	v_lshl_add_u64 v[40:41], v[64:65], 1, v[34:35]
	global_load_dwordx2 v[66:67], v[40:41], off nt
	v_lshrrev_b32_e32 v32, 3, v36
	v_add_u32_e32 v32, 16, v32
	v_cndmask_b32_e32 v32, v32, v119, vcc
	v_mad_i64_i32 v[44:45], s[0:1], v32, s38, v[144:145]
	global_load_dwordx4 v[32:35], v[44:45], off
	global_load_dwordx2 v[68:69], v[40:41], off offset:32 nt
	global_load_dwordx4 v[36:39], v[44:45], off offset:64
	global_load_dwordx2 v[70:71], v[40:41], off offset:256 nt
	global_load_dwordx2 v[72:73], v[40:41], off offset:288 nt
	s_nop 0
	global_load_dwordx4 v[40:43], v[44:45], off offset:512
	s_nop 0
	global_load_dwordx4 v[44:47], v[44:45], off offset:576
	v_lshrrev_b32_e32 v48, 3, v52
	global_load_dwordx2 v[76:77], v[60:61], off nt
	v_add_u32_e32 v48, 16, v48
	v_cndmask_b32_e64 v48, v48, v119, s[6:7]
	v_mad_i64_i32 v[62:63], s[0:1], v48, s38, v[144:145]
	global_load_dwordx4 v[48:51], v[62:63], off
	global_load_dwordx2 v[78:79], v[60:61], off offset:32 nt
	global_load_dwordx4 v[52:55], v[62:63], off offset:64
	global_load_dwordx2 v[80:81], v[60:61], off offset:256 nt
	global_load_dwordx4 v[56:59], v[62:63], off offset:512
	global_load_dwordx2 v[82:83], v[60:61], off offset:288 nt
	s_nop 0
	global_load_dwordx4 v[60:63], v[62:63], off offset:576
	v_cndmask_b32_e32 v85, v158, v159, vcc
	v_cndmask_b32_e32 v84, v160, v161, vcc
	v_lshl_add_u64 v[64:65], v[64:65], 2, v[84:85]
	v_cndmask_b32_e64 v85, v158, v159, s[6:7]
	v_cndmask_b32_e64 v84, v160, v161, s[6:7]
	v_lshl_add_u64 v[74:75], v[74:75], 2, v[84:85]
	s_andn2_b64 vcc, exec, s[4:5]
	s_mov_b64 s[4:5], -1
	s_waitcnt vmcnt(15)
	v_lshlrev_b32_e32 v84, 16, v66
	v_and_b32_e32 v85, 0xffff0000, v66
	v_lshlrev_b32_e32 v66, 16, v67
	v_and_b32_e32 v67, 0xffff0000, v67
	s_waitcnt vmcnt(14)
	v_pk_fma_f32 v[30:31], v[30:31], v[34:35], v[66:67]
	v_pk_fma_f32 v[28:29], v[28:29], v[32:33], v[84:85]
	global_store_dwordx4 v[64:65], v[28:31], off nt
	s_waitcnt vmcnt(14)
	s_nop 0
	v_lshlrev_b32_e32 v28, 16, v68
	v_and_b32_e32 v29, 0xffff0000, v68
	v_lshlrev_b32_e32 v30, 16, v69
	v_and_b32_e32 v31, 0xffff0000, v69
	s_waitcnt vmcnt(13)
	v_pk_fma_f32 v[26:27], v[26:27], v[38:39], v[30:31]
	v_pk_fma_f32 v[24:25], v[24:25], v[36:37], v[28:29]
	global_store_dwordx4 v[64:65], v[24:27], off offset:64 nt
	s_waitcnt vmcnt(13)
	s_nop 0
	v_lshlrev_b32_e32 v24, 16, v70
	v_and_b32_e32 v25, 0xffff0000, v70
	v_lshlrev_b32_e32 v26, 16, v71
	v_and_b32_e32 v27, 0xffff0000, v71
	s_waitcnt vmcnt(11)
	v_pk_fma_f32 v[22:23], v[22:23], v[42:43], v[26:27]
	v_pk_fma_f32 v[20:21], v[20:21], v[40:41], v[24:25]
	global_store_dwordx4 v[64:65], v[20:23], off offset:512 nt
	s_nop 1
	v_lshlrev_b32_e32 v20, 16, v72
	v_and_b32_e32 v21, 0xffff0000, v72
	v_lshlrev_b32_e32 v22, 16, v73
	v_and_b32_e32 v23, 0xffff0000, v73
	s_waitcnt vmcnt(11)
	v_pk_fma_f32 v[14:15], v[14:15], v[46:47], v[22:23]
	v_pk_fma_f32 v[12:13], v[12:13], v[44:45], v[20:21]
	global_store_dwordx4 v[64:65], v[12:15], off offset:576 nt
	s_waitcnt vmcnt(11)
	s_nop 0
	v_lshlrev_b32_e32 v12, 16, v76
	v_and_b32_e32 v13, 0xffff0000, v76
	v_lshlrev_b32_e32 v14, 16, v77
	v_and_b32_e32 v15, 0xffff0000, v77
	s_waitcnt vmcnt(10)
	v_pk_fma_f32 v[14:15], v[18:19], v[50:51], v[14:15]
	v_pk_fma_f32 v[12:13], v[16:17], v[48:49], v[12:13]
	global_store_dwordx4 v[74:75], v[12:15], off nt
	s_waitcnt vmcnt(10)
	s_nop 0
	v_lshlrev_b32_e32 v12, 16, v78
	v_and_b32_e32 v13, 0xffff0000, v78
	v_lshlrev_b32_e32 v14, 16, v79
	v_and_b32_e32 v15, 0xffff0000, v79
	s_waitcnt vmcnt(9)
	v_pk_fma_f32 v[10:11], v[10:11], v[54:55], v[14:15]
	v_pk_fma_f32 v[8:9], v[8:9], v[52:53], v[12:13]
	global_store_dwordx4 v[74:75], v[8:11], off offset:64 nt
	s_waitcnt vmcnt(9)
	s_nop 0
	v_lshlrev_b32_e32 v8, 16, v80
	v_and_b32_e32 v9, 0xffff0000, v80
	v_lshlrev_b32_e32 v10, 16, v81
	v_and_b32_e32 v11, 0xffff0000, v81
	s_waitcnt vmcnt(8)
	v_pk_fma_f32 v[6:7], v[6:7], v[58:59], v[10:11]
	v_pk_fma_f32 v[4:5], v[4:5], v[56:57], v[8:9]
	global_store_dwordx4 v[74:75], v[4:7], off offset:512 nt
	s_waitcnt vmcnt(8)
	s_nop 0
	v_lshlrev_b32_e32 v4, 16, v82
	v_and_b32_e32 v5, 0xffff0000, v82
	v_lshlrev_b32_e32 v6, 16, v83
	v_and_b32_e32 v7, 0xffff0000, v83
	s_waitcnt vmcnt(7)
	v_pk_fma_f32 v[2:3], v[2:3], v[62:63], v[6:7]
	v_pk_fma_f32 v[0:1], v[0:1], v[60:61], v[4:5]
	global_store_dwordx4 v[74:75], v[0:3], off offset:576 nt
	s_cbranch_vccnz .LBB0_2137
	s_andn2_b64 vcc, exec, s[10:11]
	s_cbranch_vccnz .LBB0_2136
	s_barrier
	s_branch .LBB0_2136
